# S5 scan phase entry: one-shot warm-up loads of the task's parameter rows (a, log_dt, B, C, d) so the set-up's serialized parameter loads hit in cache
# speedup vs baseline: 1.0051x; 1.0051x over previous
.LBB0_790:
	s_or_b64 exec, exec, s[8:9]
	s_lshr_b32 s6, s68, 8
	s_lshl_b32 s7, s2, 1
	s_waitcnt lgkmcnt(0)
	s_barrier
	v_mbcnt_lo_u32_b32 v0, -1, 0
	v_mbcnt_hi_u32_b32 v0, -1, v0
	s_add_i32 s46, s6, s7
	v_add_u32_e32 v0, s3, v0
	s_mov_b64 s[8:9], s[0:1]
	s_cmpk_gt_i32 s46, 0x1ff
	s_cbranch_scc1 .LBB0_881
	s_and_b32 s100, s46, 0x7f
	v_mbcnt_lo_u32_b32 v184, -1, 0
	v_mbcnt_hi_u32_b32 v184, -1, v184
	s_lshl_b32 s101, s100, 12
	v_lshl_add_u32 v185, v184, 6, s101
	s_lshl_b32 s101, s100, 8
	v_lshl_add_u32 v186, v184, 2, s101
	s_lshl_b32 s101, s100, 6
	v_and_b32_e32 v187, 15, v184
	v_lshl_add_u32 v187, v187, 2, s101
	s_lshl_b32 s101, s100, 2
	v_mov_b32_e32 v188, s101
	s_load_dwordx2 s[98:99], s[0:1], 0x80
	s_waitcnt lgkmcnt(0)
	global_load_dword v189, v185, s[98:99]
	s_load_dwordx2 s[98:99], s[0:1], 0x88
	s_waitcnt lgkmcnt(0)
	global_load_dword v190, v185, s[98:99]
	s_load_dwordx2 s[98:99], s[0:1], 0x90
	s_waitcnt lgkmcnt(0)
	global_load_dword v191, v185, s[98:99]
	s_load_dwordx2 s[98:99], s[0:1], 0x98
	s_waitcnt lgkmcnt(0)
	global_load_dword v192, v185, s[98:99]
	s_load_dwordx2 s[98:99], s[0:1], 0x68
	s_waitcnt lgkmcnt(0)
	global_load_dword v193, v186, s[98:99]
	s_load_dwordx2 s[98:99], s[0:1], 0x70
	s_waitcnt lgkmcnt(0)
	global_load_dword v194, v186, s[98:99]
	s_load_dwordx2 s[98:99], s[0:1], 0xa0
	s_waitcnt lgkmcnt(0)
	global_load_dword v195, v187, s[98:99]
	s_load_dwordx2 s[98:99], s[0:1], 0x78
	s_waitcnt lgkmcnt(0)
	global_load_dword v196, v188, s[98:99]
	s_load_dwordx2 s[52:53], s[8:9], 0xe0
	v_and_b32_e32 v117, 63, v0
	v_or_b32_e32 v5, 48, v117
	v_mul_u32_u24_e32 v142, 0x50, v5
	v_or_b32_e32 v5, 0x70, v117
	s_waitcnt lgkmcnt(0)
	s_add_u32 s56, s52, 0x11800000
	s_addc_u32 s57, s53, 0
	s_add_u32 s58, s52, 0x17000000
	s_addc_u32 s59, s53, 0
	s_lshl_b32 s8, s69, 9
	s_add_i32 s30, 0, 0x20800
	s_and_b32 s8, s8, 0xfffff800
	s_mulk_i32 s69, 0x4100
	s_bfe_u32 s85, s68, 0x20006
	s_add_i32 s12, s30, s8
	s_add_i32 s86, s69, 0
	s_cmp_lg_u32 s85, 3
	v_mul_u32_u24_e32 v143, 0x50, v5
	v_bfe_u32 v5, v0, 3, 3
	v_bfe_u32 v1, v0, 4, 2
	s_cselect_b64 s[60:61], -1, 0
	s_lshl_b32 s87, s85, 9
	v_and_b32_e32 v144, 6, v5
	v_lshl_add_u32 v12, v5, 4, s86
	v_lshlrev_b32_e32 v146, 2, v5
	v_or_b32_e32 v5, 8, v5
	v_and_b32_e32 v136, 15, v0
	v_lshlrev_b32_e32 v116, 3, v1
	v_mov_b32_e32 v9, s86
	s_movk_i32 s13, 0x110
	v_lshl_add_u32 v13, v5, 4, s86
	v_lshlrev_b32_e32 v147, 2, v5
	s_add_i32 s12, s12, s87
	v_lshlrev_b32_e32 v5, 3, v117
	v_cmp_gt_u32_e64 s[8:9], 32, v117
	v_lshlrev_b32_e32 v7, 2, v117
	v_add_u32_e32 v148, s12, v5
	s_cmp_lg_u32 s85, 0
	v_mad_u32_u24 v150, v136, s13, v9
	s_movk_i32 s12, 0xfef2
	v_cmp_eq_u32_e32 vcc, v116, v136
	v_or_b32_e32 v19, 1, v116
	v_and_b32_e32 v6, 60, v7
	s_cselect_b64 s[62:63], -1, 0
	v_add_u32_e32 v149, s86, v7
	v_mad_i32_i24 v7, v136, s12, v150
	s_and_b64 s[12:13], s[8:9], vcc
	v_cmp_eq_u32_e32 vcc, v19, v136
	v_or_b32_e32 v19, 2, v116
	s_and_b64 s[14:15], s[8:9], vcc
	v_cmp_eq_u32_e32 vcc, v19, v136
	v_or_b32_e32 v19, 3, v116
	s_and_b64 s[16:17], s[8:9], vcc
	v_cmp_eq_u32_e32 vcc, v19, v136
	v_or_b32_e32 v19, 4, v116
	s_and_b64 s[18:19], s[8:9], vcc
	v_cmp_eq_u32_e32 vcc, v19, v136
	v_or_b32_e32 v19, 5, v116
	s_and_b64 s[20:21], s[8:9], vcc
	v_cmp_eq_u32_e32 vcc, v19, v136
	v_or_b32_e32 v19, 6, v116
	v_writelane_b32 v255, s91, 12
	v_lshlrev_b32_e32 v2, 6, v136
	v_lshlrev_b32_e32 v4, 3, v0
	v_and_b32_e32 v11, 7, v0
	v_and_b32_e32 v14, 0x1e0, v5
	s_and_b64 s[22:23], s[8:9], vcc
	v_cmp_eq_u32_e32 vcc, v19, v136
	v_or_b32_e32 v19, 7, v116
	s_lshl_b32 s34, s6, 4
	s_add_i32 s91, s6, s7
	s_lshl_b32 s6, s6, 11
	v_mov_b32_e32 v119, 0
	v_lshl_or_b32 v3, v1, 2, v2
	v_and_b32_e32 v2, 8, v116
	v_and_b32_e32 v4, 8, v4
	v_and_b32_e32 v138, 48, v0
	v_lshlrev_b32_e32 v145, 1, v1
	v_lshl_add_u32 v10, v6, 2, s86
	v_mul_u32_u24_e32 v1, 0x110, v1
	v_lshlrev_b32_e32 v8, 3, v11
	v_mul_u32_u24_e32 v11, 0x440, v11
	v_mul_u32_u24_e32 v9, 12, v117
	v_and_b32_e32 v15, 0x180, v5
	v_or_b32_e32 v16, 0x60, v14
	v_or_b32_e32 v17, 0x260, v14
	v_or_b32_e32 v18, 0x460, v14
	v_or_b32_e32 v14, 0x660, v14
	s_and_b64 s[24:25], s[8:9], vcc
	v_cmp_eq_u32_e32 vcc, v19, v136
	v_and_b32_e32 v118, 16, v0
	s_lshl_b32 s31, s2, 5
	s_add_i32 s30, s30, s6
	s_mov_b32 s55, 0
	v_bfe_u32 v137, v0, 1, 5
	v_cmp_lt_u32_e64 s[10:11], 31, v117
	v_add_u32_e32 v139, s86, v138
	v_mul_u32_u24_e32 v140, 0x50, v117
	v_mul_u32_u24_e32 v141, 0x50, v136
	s_and_b64 s[26:27], s[8:9], vcc
	s_lshl_b32 s88, s42, 1
	v_lshl_add_u64 v[120:121], s[52:53], 0, v[118:119]
	v_or_b32_e32 v151, s87, v136
	s_add_i32 s89, s31, s34
	s_lshl_b32 s90, s42, 5
	v_add_u32_e32 v152, s30, v5
	s_mov_b32 s92, 0x3fb8aa3b
	s_brev_b32 s93, 18
	s_mov_b32 s94, 0xfe5163ab
	s_mov_b32 s95, 0x3c439041
	s_mov_b32 s96, 0xdb629599
	s_mov_b32 s97, 0xf534ddc0
	s_mov_b32 s81, 0xfc2757d1
	s_mov_b32 s82, 0x4e441529
	s_mov_b32 s83, 0xa2f9836e
	s_mov_b32 s72, 0x3fc90fda
	s_mov_b32 s48, 0x3f22f983
	s_mov_b32 s49, 0xbfc90fda
	s_mov_b32 s6, 0xc2ce8ed0
	s_mov_b32 s7, 0x42b17218
	s_movk_i32 s44, 0x1f8
	v_mov_b32_e32 v153, 0x3c0881c4
	v_mov_b32_e32 v154, 0xbab64f3b
	s_brev_b32 s45, 1
	v_lshlrev_b32_e32 v155, 2, v3
	v_lshlrev_b32_e32 v122, 1, v2
	v_lshlrev_b32_e32 v118, 2, v6
	v_add_u32_e32 v156, v10, v1
	v_lshlrev_b32_e32 v124, 1, v8
	v_add_u32_e32 v157, v12, v11
	v_add_u32_e32 v158, v13, v11
	v_lshlrev_b32_e32 v126, 1, v4
	v_add_u32_e32 v159, v149, v9
	v_add_u32_e32 v160, v7, v15
	v_add_u32_e32 v161, v7, v16
	v_add_u32_e32 v162, v7, v17
	v_add_u32_e32 v163, v7, v18
	v_add_u32_e32 v164, v7, v14
	v_not_b32_e32 v165, 63
	v_not_b32_e32 v166, 31
	v_mov_b32_e32 v167, 0x7f800000
	v_mov_b32_e32 v168, 0x7fc00000
	s_mov_b32 s84, s46
	s_branch .LBB0_793
